# rg_conv: items software-pipelined two deep (next item's 14 loads issued before the current item's math), unpredicated tap loads zeroed after
# baseline (speedup 1.0000x reference)
; __device__ __forceinline__ unsigned pk2(float lo, float hi) { f32x2_pk v = {lo, hi}; bf16x2_pk b = __builtin_convertvector(v, bf16x2_pk); return __builtin_bit_cast(unsigned, b); }
; __device__ __forceinline__ void rg_conv_phase(const bf16_t* XR, bf16_t* XCV, const float* cw, const float* cb, int gtid, int ngt) {
;     for (int it = gtid; it < MT * 160; it += ngt) { const int m = it / 160, c8 = (it % 160) * 8;
;         int t, L; if (m < ML) { t = m & 2047; L = SEQ; } else { t = (m - ML) & 255; L = CTX; }
;         float o[8];
; #pragma unroll
;         for (int e = 0; e < 8; ++e) o[e] = cb[c8 + e];
; #pragma unroll
;         for (int k = 0; k < 4; ++k) { const int tt = t + k - 2; if (tt < 0 || tt >= L) continue;
;             const u32x4 w = *(const u32x4*)(XR + (size_t)(m + k - 2) * DRNN + c8); const float* wk = cw + k * DRNN + c8;
;             o[0] += wk[0] * bflo(w.x); o[1] += wk[1] * bfhi(w.x); o[2] += wk[2] * bflo(w.y); o[3] += wk[3] * bfhi(w.y); o[4] += wk[4] * bflo(w.z); o[5] += wk[5] * bfhi(w.z); o[6] += wk[6] * bflo(w.w); o[7] += wk[7] * bfhi(w.w); }
;         u32x4 r; r.x = pk2(o[0], o[1]); r.y = pk2(o[2], o[3]); r.z = pk2(o[4], o[5]); r.w = pk2(o[6], o[7]);
;         *(u32x4*)(XCV + (size_t)m * DRNN + c8) = r; }
; }
.LBB0_814:
	s_add_i32 s1, s75, 1
	s_cmp_le_i32 s70, s1
	s_cselect_b64 s[2:3], -1, 0
	s_cmp_lt_i32 s1, s71
	s_cselect_b64 s[6:7], -1, 0
	s_and_b64 s[2:3], s[2:3], s[6:7]
	s_andn2_b64 vcc, exec, s[2:3]
	s_cbranch_vccnz .LBB0_827
	v_mov_b32_e32 v0, v198
	s_mov_b32 s2, s91
	s_mov_b64 s[6:7], s[84:85]
	v_lshl_add_u32 v9, s2, 9, v0
	s_mov_b32 s2, 0x5a0000
	v_cmp_gt_i32_e32 vcc, s2, v9
	s_and_saveexec_b64 s[16:17], vcc
	s_cbranch_execz .LBB0_826
	s_load_dwordx4 s[8:11], s[6:7], 0x120
	s_load_dwordx4 s[12:15], s[6:7], 0x48
	v_lshlrev_b32_e32 v8, 3, v9
	s_mov_b64 s[18:19], 0
	s_waitcnt lgkmcnt(0)
	s_add_u32 s10, s10, 0x8a00000
	s_addc_u32 s11, s11, 0
	s_lshl_b32 s2, s33, 3
	v_mov_b32_e32 v140, v9
	v_mov_b32_e32 v142, v8
	s_movk_i32 s18, 22
	v_mul_hi_i32 v128, v140, s43
	v_lshrrev_b32_e32 v129, 31, v128
	v_ashrrev_i32_e32 v128, 6, v128
	v_add_u32_e32 v56, v128, v129
	s_movk_i32 s3, 0xfb00
	v_mad_u64_u32 v[60:61], s[6:7], v56, s3, v[142:143]
	v_ashrrev_i32_e32 v61, 31, v60
	v_lshlrev_b64 v[130:131], 2, v[60:61]
	v_lshl_add_u64 v[132:133], s[14:15], 0, v[130:131]
	global_load_dwordx4 v[0:3], v[132:133], off offset:16
	global_load_dwordx4 v[4:7], v[132:133], off
	s_mov_b32 s3, 0x500000
	v_cmp_gt_i32_e32 vcc, s3, v140
	v_mov_b32_e32 v134, 0x7ff
	v_mov_b32_e32 v135, 0x802
	v_cndmask_b32_e32 v134, v216, v134, vcc
	v_and_b32_e32 v57, v134, v56
	v_bfrev_b32_e32 v134, 4.0
	v_cndmask_b32_e32 v58, v134, v135, vcc
	v_lshl_add_u64 v[136:137], v[60:61], 1, s[8:9]
	v_lshl_add_u64 v[130:131], s[12:13], 0, v[130:131]
	s_movk_i32 s3, 0xa00
	v_cmp_lt_u32_e32 vcc, 1, v57
	v_cmp_lt_u32_e64 s[6:7], v57, v58
	v_add_u32_e32 v138, -2, v56
	s_nop 1
	s_and_b64 vcc, vcc, s[6:7]
	s_nop 1
	v_cndmask_b32_e32 v138, v56, v138, vcc
	v_mad_i64_i32 v[128:129], s[20:21], v138, s3, v[136:137]
	global_load_dwordx4 v[8:11], v[128:129], off
	v_add_u32_e32 v139, 1, v57
	v_cmp_ne_u32_e32 vcc, 0, v57
	v_cmp_lt_u32_e64 s[6:7], v139, v58
	v_add_u32_e32 v138, -1, v56
	s_nop 1
	s_and_b64 vcc, vcc, s[6:7]
	s_nop 1
	v_cndmask_b32_e32 v138, v56, v138, vcc
	v_mad_i64_i32 v[128:129], s[20:21], v138, s3, v[136:137]
	global_load_dwordx4 v[12:15], v[128:129], off
	v_mad_i64_i32 v[128:129], s[20:21], v56, s3, v[136:137]
	global_load_dwordx4 v[16:19], v[128:129], off
	v_add_u32_e32 v139, 3, v57
	v_add_u32_e32 v138, 1, v56
	v_cmp_lt_u32_e32 vcc, v139, v58
	s_nop 1
	v_cndmask_b32_e32 v138, v56, v138, vcc
	v_mad_i64_i32 v[128:129], s[20:21], v138, s3, v[136:137]
	global_load_dwordx4 v[20:23], v[128:129], off
	global_load_dwordx4 v[24:27], v[130:131], off
	global_load_dwordx4 v[28:31], v[130:131], off offset:16
	s_mov_b64 s[100:101], 0x1000
	v_lshl_add_u64 v[128:129], v[130:131], 0, s[100:101]
	global_load_dwordx4 v[32:35], v[128:129], off offset:1024
	global_load_dwordx4 v[36:39], v[128:129], off offset:1040
	s_mov_b64 s[100:101], 0x2000
	v_lshl_add_u64 v[128:129], v[130:131], 0, s[100:101]
	global_load_dwordx4 v[40:43], v[128:129], off offset:2048
	global_load_dwordx4 v[44:47], v[128:129], off offset:2064
	s_mov_b64 s[100:101], 0x3000
	v_lshl_add_u64 v[128:129], v[130:131], 0, s[100:101]
	global_load_dwordx4 v[48:51], v[128:129], off offset:3072
	global_load_dwordx4 v[52:55], v[128:129], off offset:3088
	v_add_u32_e32 v140, s33, v140
	v_add_u32_e32 v142, s2, v142
.Lconv_loop:
	v_mul_hi_i32 v128, v140, s43
	v_lshrrev_b32_e32 v129, 31, v128
	v_ashrrev_i32_e32 v128, 6, v128
	v_add_u32_e32 v120, v128, v129
	s_movk_i32 s3, 0xfb00
	v_mad_u64_u32 v[124:125], s[6:7], v120, s3, v[142:143]
	v_ashrrev_i32_e32 v125, 31, v124
	v_lshlrev_b64 v[130:131], 2, v[124:125]
	v_lshl_add_u64 v[132:133], s[14:15], 0, v[130:131]
	global_load_dwordx4 v[64:67], v[132:133], off offset:16
	global_load_dwordx4 v[68:71], v[132:133], off
	s_mov_b32 s3, 0x500000
	v_cmp_gt_i32_e32 vcc, s3, v140
	v_mov_b32_e32 v134, 0x7ff
	v_mov_b32_e32 v135, 0x802
	v_cndmask_b32_e32 v134, v216, v134, vcc
	v_and_b32_e32 v121, v134, v120
	v_bfrev_b32_e32 v134, 4.0
	v_cndmask_b32_e32 v122, v134, v135, vcc
	v_lshl_add_u64 v[136:137], v[124:125], 1, s[8:9]
	v_lshl_add_u64 v[130:131], s[12:13], 0, v[130:131]
	s_movk_i32 s3, 0xa00
	v_cmp_lt_u32_e32 vcc, 1, v121
	v_cmp_lt_u32_e64 s[6:7], v121, v122
	v_add_u32_e32 v138, -2, v120
	s_nop 1
	s_and_b64 vcc, vcc, s[6:7]
	s_nop 1
	v_cndmask_b32_e32 v138, v120, v138, vcc
	v_mad_i64_i32 v[128:129], s[20:21], v138, s3, v[136:137]
	global_load_dwordx4 v[72:75], v[128:129], off
	v_add_u32_e32 v139, 1, v121
	v_cmp_ne_u32_e32 vcc, 0, v121
	v_cmp_lt_u32_e64 s[6:7], v139, v122
	v_add_u32_e32 v138, -1, v120
	s_nop 1
	s_and_b64 vcc, vcc, s[6:7]
	s_nop 1
	v_cndmask_b32_e32 v138, v120, v138, vcc
	v_mad_i64_i32 v[128:129], s[20:21], v138, s3, v[136:137]
	global_load_dwordx4 v[76:79], v[128:129], off
	v_mad_i64_i32 v[128:129], s[20:21], v120, s3, v[136:137]
	global_load_dwordx4 v[80:83], v[128:129], off
	v_add_u32_e32 v139, 3, v121
	v_add_u32_e32 v138, 1, v120
	v_cmp_lt_u32_e32 vcc, v139, v122
	s_nop 1
	v_cndmask_b32_e32 v138, v120, v138, vcc
	v_mad_i64_i32 v[128:129], s[20:21], v138, s3, v[136:137]
	global_load_dwordx4 v[84:87], v[128:129], off
	global_load_dwordx4 v[88:91], v[130:131], off
	global_load_dwordx4 v[92:95], v[130:131], off offset:16
	s_mov_b64 s[100:101], 0x1000
	v_lshl_add_u64 v[128:129], v[130:131], 0, s[100:101]
	global_load_dwordx4 v[96:99], v[128:129], off offset:1024
	global_load_dwordx4 v[100:103], v[128:129], off offset:1040
	s_mov_b64 s[100:101], 0x2000
	v_lshl_add_u64 v[128:129], v[130:131], 0, s[100:101]
	global_load_dwordx4 v[104:107], v[128:129], off offset:2048
	global_load_dwordx4 v[108:111], v[128:129], off offset:2064
	s_mov_b64 s[100:101], 0x3000
	v_lshl_add_u64 v[128:129], v[130:131], 0, s[100:101]
	global_load_dwordx4 v[112:115], v[128:129], off offset:3072
	global_load_dwordx4 v[116:119], v[128:129], off offset:3088
	v_add_u32_e32 v140, s33, v140
	v_add_u32_e32 v142, s2, v142
	s_waitcnt vmcnt(14)
; __device__ __forceinline__ unsigned pk2(float lo, float hi) { f32x2_pk v = {lo, hi}; bf16x2_pk b = __builtin_convertvector(v, bf16x2_pk); return __builtin_bit_cast(unsigned, b); }
; __device__ __forceinline__ void rg_conv_phase(const bf16_t* XR, bf16_t* XCV, const float* cw, const float* cb, int gtid, int ngt) {
;     ...
;         for (int k = 0; k < 4; ++k) { const int tt = t + k - 2; if (tt < 0 || tt >= L) continue;
;             const u32x4 w = *(const u32x4*)(XR + (size_t)(m + k - 2) * DRNN + c8); const float* wk = cw + k * DRNN + c8;
;             o[0] += wk[0] * bflo(w.x); o[1] += wk[1] * bfhi(w.x); o[2] += wk[2] * bflo(w.y); o[3] += wk[3] * bfhi(w.y); o[4] += wk[4] * bflo(w.z); o[5] += wk[5] * bfhi(w.z); o[6] += wk[6] * bflo(w.w); o[7] += wk[7] * bfhi(w.w); }
;         u32x4 r; r.x = pk2(o[0], o[1]); r.y = pk2(o[2], o[3]); r.z = pk2(o[4], o[5]); r.w = pk2(o[6], o[7]);
;         *(u32x4*)(XCV + (size_t)m * DRNN + c8) = r; }
	v_cmp_lt_u32_e32 vcc, 1, v57
	v_cmp_lt_u32_e64 s[6:7], v57, v58
	v_add_u32_e32 v139, 1, v57
	s_nop 1
	s_and_b64 vcc, vcc, s[6:7]
	s_nop 1
	v_cndmask_b32_e32 v8, 0, v8, vcc
	v_cndmask_b32_e32 v9, 0, v9, vcc
	v_cndmask_b32_e32 v10, 0, v10, vcc
	v_cndmask_b32_e32 v11, 0, v11, vcc
	v_cmp_ne_u32_e32 vcc, 0, v57
	v_cmp_lt_u32_e64 s[6:7], v139, v58
	v_add_u32_e32 v138, 2, v57
	s_nop 1
	s_and_b64 vcc, vcc, s[6:7]
	s_nop 1
	v_cndmask_b32_e32 v12, 0, v12, vcc
	v_cndmask_b32_e32 v13, 0, v13, vcc
	v_cndmask_b32_e32 v14, 0, v14, vcc
	v_cndmask_b32_e32 v15, 0, v15, vcc
	v_cmp_lt_u32_e32 vcc, v138, v58
	v_add_u32_e32 v139, 3, v57
	s_nop 1
	v_cndmask_b32_e32 v16, 0, v16, vcc
	v_cndmask_b32_e32 v17, 0, v17, vcc
	v_cndmask_b32_e32 v18, 0, v18, vcc
	v_cndmask_b32_e32 v19, 0, v19, vcc
	v_cmp_lt_u32_e32 vcc, v139, v58
	s_nop 1
	s_nop 0
	v_cndmask_b32_e32 v20, 0, v20, vcc
	v_cndmask_b32_e32 v21, 0, v21, vcc
	v_cndmask_b32_e32 v22, 0, v22, vcc
	v_cndmask_b32_e32 v23, 0, v23, vcc
	v_lshlrev_b32_e32 v138, 16, v8
	v_and_b32_e32 v139, 0xffff0000, v8
	v_pk_fma_f32 v[4:5], v[24:25], v[138:139], v[4:5]
	v_lshlrev_b32_e32 v138, 16, v9
	v_and_b32_e32 v139, 0xffff0000, v9
	v_pk_fma_f32 v[6:7], v[26:27], v[138:139], v[6:7]
	v_lshlrev_b32_e32 v138, 16, v10
	v_and_b32_e32 v139, 0xffff0000, v10
	v_pk_fma_f32 v[0:1], v[28:29], v[138:139], v[0:1]
	v_lshlrev_b32_e32 v138, 16, v11
	v_and_b32_e32 v139, 0xffff0000, v11
	v_pk_fma_f32 v[2:3], v[30:31], v[138:139], v[2:3]
	v_lshlrev_b32_e32 v138, 16, v12
	v_and_b32_e32 v139, 0xffff0000, v12
	v_pk_fma_f32 v[4:5], v[32:33], v[138:139], v[4:5]
	v_lshlrev_b32_e32 v138, 16, v13
	v_and_b32_e32 v139, 0xffff0000, v13
	v_pk_fma_f32 v[6:7], v[34:35], v[138:139], v[6:7]
	v_lshlrev_b32_e32 v138, 16, v14
	v_and_b32_e32 v139, 0xffff0000, v14
	v_pk_fma_f32 v[0:1], v[36:37], v[138:139], v[0:1]
	v_lshlrev_b32_e32 v138, 16, v15
	v_and_b32_e32 v139, 0xffff0000, v15
	v_pk_fma_f32 v[2:3], v[38:39], v[138:139], v[2:3]
	v_lshlrev_b32_e32 v138, 16, v16
	v_and_b32_e32 v139, 0xffff0000, v16
	v_pk_fma_f32 v[4:5], v[40:41], v[138:139], v[4:5]
	v_lshlrev_b32_e32 v138, 16, v17
	v_and_b32_e32 v139, 0xffff0000, v17
	v_pk_fma_f32 v[6:7], v[42:43], v[138:139], v[6:7]
	v_lshlrev_b32_e32 v138, 16, v18
	v_and_b32_e32 v139, 0xffff0000, v18
	v_pk_fma_f32 v[0:1], v[44:45], v[138:139], v[0:1]
	v_lshlrev_b32_e32 v138, 16, v19
	v_and_b32_e32 v139, 0xffff0000, v19
	v_pk_fma_f32 v[2:3], v[46:47], v[138:139], v[2:3]
	v_lshlrev_b32_e32 v138, 16, v20
	v_and_b32_e32 v139, 0xffff0000, v20
	v_pk_fma_f32 v[4:5], v[48:49], v[138:139], v[4:5]
	v_lshlrev_b32_e32 v138, 16, v21
	v_and_b32_e32 v139, 0xffff0000, v21
	v_pk_fma_f32 v[6:7], v[50:51], v[138:139], v[6:7]
	v_lshlrev_b32_e32 v138, 16, v22
	v_and_b32_e32 v139, 0xffff0000, v22
	v_pk_fma_f32 v[0:1], v[52:53], v[138:139], v[0:1]
	v_lshlrev_b32_e32 v138, 16, v23
	v_and_b32_e32 v139, 0xffff0000, v23
	v_pk_fma_f32 v[2:3], v[54:55], v[138:139], v[2:3]
	v_cvt_pk_bf16_f32 v128, v4, v5
	v_cvt_pk_bf16_f32 v129, v6, v7
	v_cvt_pk_bf16_f32 v130, v0, v1
	v_cvt_pk_bf16_f32 v131, v2, v3
	v_mov_b64_e32 v[132:133], s[10:11]
	s_movk_i32 s3, 0xa00
	v_mad_i64_i32 v[132:133], s[6:7], v56, s3, v[132:133]
	v_lshl_add_u64 v[132:133], v[60:61], 1, v[132:133]
	global_store_dwordx4 v[132:133], v[128:131], off
	s_nop 1
	v_mul_hi_i32 v128, v140, s43
	v_lshrrev_b32_e32 v129, 31, v128
	v_ashrrev_i32_e32 v128, 6, v128
	v_add_u32_e32 v56, v128, v129
	s_movk_i32 s3, 0xfb00
	v_mad_u64_u32 v[60:61], s[6:7], v56, s3, v[142:143]
	v_ashrrev_i32_e32 v61, 31, v60
	v_lshlrev_b64 v[130:131], 2, v[60:61]
	v_lshl_add_u64 v[132:133], s[14:15], 0, v[130:131]
	global_load_dwordx4 v[0:3], v[132:133], off offset:16
	global_load_dwordx4 v[4:7], v[132:133], off
	s_mov_b32 s3, 0x500000
	v_cmp_gt_i32_e32 vcc, s3, v140
	v_mov_b32_e32 v134, 0x7ff
	v_mov_b32_e32 v135, 0x802
	v_cndmask_b32_e32 v134, v216, v134, vcc
	v_and_b32_e32 v57, v134, v56
	v_bfrev_b32_e32 v134, 4.0
	v_cndmask_b32_e32 v58, v134, v135, vcc
	v_lshl_add_u64 v[136:137], v[60:61], 1, s[8:9]
	v_lshl_add_u64 v[130:131], s[12:13], 0, v[130:131]
	s_movk_i32 s3, 0xa00
	v_cmp_lt_u32_e32 vcc, 1, v57
	v_cmp_lt_u32_e64 s[6:7], v57, v58
	v_add_u32_e32 v138, -2, v56
	s_nop 1
	s_and_b64 vcc, vcc, s[6:7]
	s_nop 1
	v_cndmask_b32_e32 v138, v56, v138, vcc
	v_mad_i64_i32 v[128:129], s[20:21], v138, s3, v[136:137]
	global_load_dwordx4 v[8:11], v[128:129], off
	v_add_u32_e32 v139, 1, v57
	v_cmp_ne_u32_e32 vcc, 0, v57
	v_cmp_lt_u32_e64 s[6:7], v139, v58
	v_add_u32_e32 v138, -1, v56
	s_nop 1
	s_and_b64 vcc, vcc, s[6:7]
	s_nop 1
	v_cndmask_b32_e32 v138, v56, v138, vcc
	v_mad_i64_i32 v[128:129], s[20:21], v138, s3, v[136:137]
	global_load_dwordx4 v[12:15], v[128:129], off
	v_mad_i64_i32 v[128:129], s[20:21], v56, s3, v[136:137]
	global_load_dwordx4 v[16:19], v[128:129], off
	v_add_u32_e32 v139, 3, v57
	v_add_u32_e32 v138, 1, v56
	v_cmp_lt_u32_e32 vcc, v139, v58
	s_nop 1
	v_cndmask_b32_e32 v138, v56, v138, vcc
	v_mad_i64_i32 v[128:129], s[20:21], v138, s3, v[136:137]
	global_load_dwordx4 v[20:23], v[128:129], off
	global_load_dwordx4 v[24:27], v[130:131], off
	global_load_dwordx4 v[28:31], v[130:131], off offset:16
	s_mov_b64 s[100:101], 0x1000
	v_lshl_add_u64 v[128:129], v[130:131], 0, s[100:101]
	global_load_dwordx4 v[32:35], v[128:129], off offset:1024
	global_load_dwordx4 v[36:39], v[128:129], off offset:1040
	s_mov_b64 s[100:101], 0x2000
	v_lshl_add_u64 v[128:129], v[130:131], 0, s[100:101]
	global_load_dwordx4 v[40:43], v[128:129], off offset:2048
	global_load_dwordx4 v[44:47], v[128:129], off offset:2064
	s_mov_b64 s[100:101], 0x3000
	v_lshl_add_u64 v[128:129], v[130:131], 0, s[100:101]
	global_load_dwordx4 v[48:51], v[128:129], off offset:3072
	global_load_dwordx4 v[52:55], v[128:129], off offset:3088
	v_add_u32_e32 v140, s33, v140
	v_add_u32_e32 v142, s2, v142
	s_waitcnt vmcnt(15)
; __device__ __forceinline__ unsigned pk2(float lo, float hi) { f32x2_pk v = {lo, hi}; bf16x2_pk b = __builtin_convertvector(v, bf16x2_pk); return __builtin_bit_cast(unsigned, b); }
; __device__ __forceinline__ void rg_conv_phase(const bf16_t* XR, bf16_t* XCV, const float* cw, const float* cb, int gtid, int ngt) {
;     for (int it = gtid; it < MT * 160; it += ngt) { const int m = it / 160, c8 = (it % 160) * 8;
;         int t, L; if (m < ML) { t = m & 2047; L = SEQ; } else { t = (m - ML) & 255; L = CTX; }
;         float o[8];
; #pragma unroll
;         for (int e = 0; e < 8; ++e) o[e] = cb[c8 + e];
; #pragma unroll
;         for (int k = 0; k < 4; ++k) { const int tt = t + k - 2; if (tt < 0 || tt >= L) continue;
;             const u32x4 w = *(const u32x4*)(XR + (size_t)(m + k - 2) * DRNN + c8); const float* wk = cw + k * DRNN + c8;
;             o[0] += wk[0] * bflo(w.x); o[1] += wk[1] * bfhi(w.x); o[2] += wk[2] * bflo(w.y); o[3] += wk[3] * bfhi(w.y); o[4] += wk[4] * bflo(w.z); o[5] += wk[5] * bfhi(w.z); o[6] += wk[6] * bflo(w.w); o[7] += wk[7] * bfhi(w.w); }
;         u32x4 r; r.x = pk2(o[0], o[1]); r.y = pk2(o[2], o[3]); r.z = pk2(o[4], o[5]); r.w = pk2(o[6], o[7]);
;         *(u32x4*)(XCV + (size_t)m * DRNN + c8) = r; }
; }
	v_cmp_lt_u32_e32 vcc, 1, v121
	v_cmp_lt_u32_e64 s[6:7], v121, v122
	v_add_u32_e32 v139, 1, v121
	s_nop 1
	s_and_b64 vcc, vcc, s[6:7]
	s_nop 1
	v_cndmask_b32_e32 v72, 0, v72, vcc
	v_cndmask_b32_e32 v73, 0, v73, vcc
	v_cndmask_b32_e32 v74, 0, v74, vcc
	v_cndmask_b32_e32 v75, 0, v75, vcc
	v_cmp_ne_u32_e32 vcc, 0, v121
	v_cmp_lt_u32_e64 s[6:7], v139, v122
	v_add_u32_e32 v138, 2, v121
	s_nop 1
	s_and_b64 vcc, vcc, s[6:7]
	s_nop 1
	v_cndmask_b32_e32 v76, 0, v76, vcc
	v_cndmask_b32_e32 v77, 0, v77, vcc
	v_cndmask_b32_e32 v78, 0, v78, vcc
	v_cndmask_b32_e32 v79, 0, v79, vcc
	v_cmp_lt_u32_e32 vcc, v138, v122
	v_add_u32_e32 v139, 3, v121
	s_nop 1
	v_cndmask_b32_e32 v80, 0, v80, vcc
	v_cndmask_b32_e32 v81, 0, v81, vcc
	v_cndmask_b32_e32 v82, 0, v82, vcc
	v_cndmask_b32_e32 v83, 0, v83, vcc
	v_cmp_lt_u32_e32 vcc, v139, v122
	s_nop 1
	s_nop 0
	v_cndmask_b32_e32 v84, 0, v84, vcc
	v_cndmask_b32_e32 v85, 0, v85, vcc
	v_cndmask_b32_e32 v86, 0, v86, vcc
	v_cndmask_b32_e32 v87, 0, v87, vcc
	v_lshlrev_b32_e32 v138, 16, v72
	v_and_b32_e32 v139, 0xffff0000, v72
	v_pk_fma_f32 v[68:69], v[88:89], v[138:139], v[68:69]
	v_lshlrev_b32_e32 v138, 16, v73
	v_and_b32_e32 v139, 0xffff0000, v73
	v_pk_fma_f32 v[70:71], v[90:91], v[138:139], v[70:71]
	v_lshlrev_b32_e32 v138, 16, v74
	v_and_b32_e32 v139, 0xffff0000, v74
	v_pk_fma_f32 v[64:65], v[92:93], v[138:139], v[64:65]
	v_lshlrev_b32_e32 v138, 16, v75
	v_and_b32_e32 v139, 0xffff0000, v75
	v_pk_fma_f32 v[66:67], v[94:95], v[138:139], v[66:67]
	v_lshlrev_b32_e32 v138, 16, v76
	v_and_b32_e32 v139, 0xffff0000, v76
	v_pk_fma_f32 v[68:69], v[96:97], v[138:139], v[68:69]
	v_lshlrev_b32_e32 v138, 16, v77
	v_and_b32_e32 v139, 0xffff0000, v77
	v_pk_fma_f32 v[70:71], v[98:99], v[138:139], v[70:71]
	v_lshlrev_b32_e32 v138, 16, v78
	v_and_b32_e32 v139, 0xffff0000, v78
	v_pk_fma_f32 v[64:65], v[100:101], v[138:139], v[64:65]
	v_lshlrev_b32_e32 v138, 16, v79
	v_and_b32_e32 v139, 0xffff0000, v79
	v_pk_fma_f32 v[66:67], v[102:103], v[138:139], v[66:67]
	v_lshlrev_b32_e32 v138, 16, v80
	v_and_b32_e32 v139, 0xffff0000, v80
	v_pk_fma_f32 v[68:69], v[104:105], v[138:139], v[68:69]
	v_lshlrev_b32_e32 v138, 16, v81
	v_and_b32_e32 v139, 0xffff0000, v81
	v_pk_fma_f32 v[70:71], v[106:107], v[138:139], v[70:71]
	v_lshlrev_b32_e32 v138, 16, v82
	v_and_b32_e32 v139, 0xffff0000, v82
	v_pk_fma_f32 v[64:65], v[108:109], v[138:139], v[64:65]
	v_lshlrev_b32_e32 v138, 16, v83
	v_and_b32_e32 v139, 0xffff0000, v83
	v_pk_fma_f32 v[66:67], v[110:111], v[138:139], v[66:67]
	v_lshlrev_b32_e32 v138, 16, v84
	v_and_b32_e32 v139, 0xffff0000, v84
	v_pk_fma_f32 v[68:69], v[112:113], v[138:139], v[68:69]
	v_lshlrev_b32_e32 v138, 16, v85
	v_and_b32_e32 v139, 0xffff0000, v85
	v_pk_fma_f32 v[70:71], v[114:115], v[138:139], v[70:71]
	v_lshlrev_b32_e32 v138, 16, v86
	v_and_b32_e32 v139, 0xffff0000, v86
	v_pk_fma_f32 v[64:65], v[116:117], v[138:139], v[64:65]
	v_lshlrev_b32_e32 v138, 16, v87
	v_and_b32_e32 v139, 0xffff0000, v87
	v_pk_fma_f32 v[66:67], v[118:119], v[138:139], v[66:67]
	v_cvt_pk_bf16_f32 v128, v68, v69
	v_cvt_pk_bf16_f32 v129, v70, v71
	v_cvt_pk_bf16_f32 v130, v64, v65
	v_cvt_pk_bf16_f32 v131, v66, v67
	v_mov_b64_e32 v[132:133], s[10:11]
	s_movk_i32 s3, 0xa00
	v_mad_i64_i32 v[132:133], s[6:7], v120, s3, v[132:133]
	v_lshl_add_u64 v[132:133], v[124:125], 1, v[132:133]
	global_store_dwordx4 v[132:133], v[128:131], off
	s_nop 1
	s_add_i32 s18, s18, -1
	s_cmp_lg_u32 s18, 0
	s_cbranch_scc1 .Lconv_loop
	s_waitcnt vmcnt(0)
	v_cmp_lt_u32_e32 vcc, 1, v57
	v_cmp_lt_u32_e64 s[6:7], v57, v58
	v_add_u32_e32 v139, 1, v57
	s_nop 1
	s_and_b64 vcc, vcc, s[6:7]
	s_nop 1
	v_cndmask_b32_e32 v8, 0, v8, vcc
	v_cndmask_b32_e32 v9, 0, v9, vcc
	v_cndmask_b32_e32 v10, 0, v10, vcc
	v_cndmask_b32_e32 v11, 0, v11, vcc
	v_cmp_ne_u32_e32 vcc, 0, v57
	v_cmp_lt_u32_e64 s[6:7], v139, v58
	v_add_u32_e32 v138, 2, v57
	s_nop 1
	s_and_b64 vcc, vcc, s[6:7]
	s_nop 1
	v_cndmask_b32_e32 v12, 0, v12, vcc
	v_cndmask_b32_e32 v13, 0, v13, vcc
	v_cndmask_b32_e32 v14, 0, v14, vcc
	v_cndmask_b32_e32 v15, 0, v15, vcc
	v_cmp_lt_u32_e32 vcc, v138, v58
	v_add_u32_e32 v139, 3, v57
	s_nop 1
	v_cndmask_b32_e32 v16, 0, v16, vcc
	v_cndmask_b32_e32 v17, 0, v17, vcc
	v_cndmask_b32_e32 v18, 0, v18, vcc
	v_cndmask_b32_e32 v19, 0, v19, vcc
	v_cmp_lt_u32_e32 vcc, v139, v58
	s_nop 1
	s_nop 0
	v_cndmask_b32_e32 v20, 0, v20, vcc
	v_cndmask_b32_e32 v21, 0, v21, vcc
	v_cndmask_b32_e32 v22, 0, v22, vcc
	v_cndmask_b32_e32 v23, 0, v23, vcc
	v_lshlrev_b32_e32 v138, 16, v8
	v_and_b32_e32 v139, 0xffff0000, v8
	v_pk_fma_f32 v[4:5], v[24:25], v[138:139], v[4:5]
	v_lshlrev_b32_e32 v138, 16, v9
	v_and_b32_e32 v139, 0xffff0000, v9
	v_pk_fma_f32 v[6:7], v[26:27], v[138:139], v[6:7]
	v_lshlrev_b32_e32 v138, 16, v10
	v_and_b32_e32 v139, 0xffff0000, v10
	v_pk_fma_f32 v[0:1], v[28:29], v[138:139], v[0:1]
	v_lshlrev_b32_e32 v138, 16, v11
	v_and_b32_e32 v139, 0xffff0000, v11
	v_pk_fma_f32 v[2:3], v[30:31], v[138:139], v[2:3]
	v_lshlrev_b32_e32 v138, 16, v12
	v_and_b32_e32 v139, 0xffff0000, v12
	v_pk_fma_f32 v[4:5], v[32:33], v[138:139], v[4:5]
	v_lshlrev_b32_e32 v138, 16, v13
	v_and_b32_e32 v139, 0xffff0000, v13
	v_pk_fma_f32 v[6:7], v[34:35], v[138:139], v[6:7]
	v_lshlrev_b32_e32 v138, 16, v14
	v_and_b32_e32 v139, 0xffff0000, v14
	v_pk_fma_f32 v[0:1], v[36:37], v[138:139], v[0:1]
	v_lshlrev_b32_e32 v138, 16, v15
	v_and_b32_e32 v139, 0xffff0000, v15
	v_pk_fma_f32 v[2:3], v[38:39], v[138:139], v[2:3]
	v_lshlrev_b32_e32 v138, 16, v16
	v_and_b32_e32 v139, 0xffff0000, v16
	v_pk_fma_f32 v[4:5], v[40:41], v[138:139], v[4:5]
	v_lshlrev_b32_e32 v138, 16, v17
	v_and_b32_e32 v139, 0xffff0000, v17
	v_pk_fma_f32 v[6:7], v[42:43], v[138:139], v[6:7]
	v_lshlrev_b32_e32 v138, 16, v18
	v_and_b32_e32 v139, 0xffff0000, v18
	v_pk_fma_f32 v[0:1], v[44:45], v[138:139], v[0:1]
	v_lshlrev_b32_e32 v138, 16, v19
	v_and_b32_e32 v139, 0xffff0000, v19
	v_pk_fma_f32 v[2:3], v[46:47], v[138:139], v[2:3]
	v_lshlrev_b32_e32 v138, 16, v20
	v_and_b32_e32 v139, 0xffff0000, v20
	v_pk_fma_f32 v[4:5], v[48:49], v[138:139], v[4:5]
	v_lshlrev_b32_e32 v138, 16, v21
	v_and_b32_e32 v139, 0xffff0000, v21
	v_pk_fma_f32 v[6:7], v[50:51], v[138:139], v[6:7]
	v_lshlrev_b32_e32 v138, 16, v22
	v_and_b32_e32 v139, 0xffff0000, v22
	v_pk_fma_f32 v[0:1], v[52:53], v[138:139], v[0:1]
	v_lshlrev_b32_e32 v138, 16, v23
	v_and_b32_e32 v139, 0xffff0000, v23
	v_pk_fma_f32 v[2:3], v[54:55], v[138:139], v[2:3]
	v_cvt_pk_bf16_f32 v128, v4, v5
	v_cvt_pk_bf16_f32 v129, v6, v7
	v_cvt_pk_bf16_f32 v130, v0, v1
	v_cvt_pk_bf16_f32 v131, v2, v3
	v_mov_b64_e32 v[132:133], s[10:11]
	s_movk_i32 s3, 0xa00
	v_mad_i64_i32 v[132:133], s[6:7], v56, s3, v[132:133]
	v_lshl_add_u64 v[132:133], v[60:61], 1, v[132:133]
	global_store_dwordx4 v[132:133], v[128:131], off
	s_nop 1
